# sample-scan tasks rewritten (all loads up front, 8 rows in lockstep) + second chunk-record loader wave + PER_S=1 rebalancing
# speedup vs baseline: 1.0253x; 1.0079x over previous
.LBB0_1087:
	s_or_b64 exec, exec, s[0:1]
	s_ashr_i32 s25, s25, 31
	s_ashr_i32 s29, s33, 31
	s_cmp_lg_u32 s52, 0
	s_cselect_b64 s[0:1], -1, 0
	s_and_b64 vcc, exec, s[0:1]
	s_cbranch_vccnz .LBB0_1175
	s_cmpk_gt_u32 s80, 0xff
	s_mov_b64 s[4:5], -1
	s_cbranch_scc0 .LBB0_1149
	s_add_i32 s4, s83, -4
	s_cmp_gt_u32 s4, 1
	s_cbranch_scc1 .LBB0_1148
	s_and_b64 vcc, exec, s[78:79]
	s_cbranch_vccnz .LBB0_1095
	s_add_i32 s4, 0, 0x241b4
	v_mov_b32_e32 v2, s4
	ds_read_b32 v2, v2
	s_waitcnt lgkmcnt(0)
	v_cmp_ne_u32_e32 vcc, 0, v2
	s_cbranch_vccnz .LBB0_1094
	v_mov_b32_e32 v2, s4

.LBB0_1094:
.LBB0_1095:
	s_add_i32 s4, s83, -4
	s_ashr_i32 s50, s82, 2
	s_cmp_gt_i32 s50, 63
	s_cbranch_scc1 .LBB0_1148
	s_add_i32 s51, s33, 3
	s_ashr_i32 s51, s51, 2
	s_mov_b32 s5, 0
	v_lshlrev_b32_e32 v214, 4, v1
.Lldr_item:
	s_mul_i32 s14, s50, 0x190000
	s_add_u32 s20, s26, 0x1d800000
	s_addc_u32 s21, s27, 0
	s_add_u32 s20, s20, s14
	s_addc_u32 s21, s21, 0
	s_add_i32 s10, s4, 0
	s_mul_i32 s14, s10, 0x3200
	s_add_u32 s18, s20, s14
	s_addc_u32 s19, s21, 0
	global_load_dwordx4 v[2:5], v214, s[18:19] offset:0
	global_load_dwordx4 v[6:9], v214, s[18:19] offset:1024
	global_load_dwordx4 v[10:13], v214, s[18:19] offset:2048
	global_load_dwordx4 v[14:17], v214, s[18:19] offset:3072
	s_add_u32 s18, s18, 0x1000
	s_addc_u32 s19, s19, 0
	global_load_dwordx4 v[18:21], v214, s[18:19] offset:0
	global_load_dwordx4 v[22:25], v214, s[18:19] offset:1024
	global_load_dwordx4 v[26:29], v214, s[18:19] offset:2048
	global_load_dwordx4 v[30:33], v214, s[18:19] offset:3072
	s_add_u32 s18, s18, 0x1000
	s_addc_u32 s19, s19, 0
	global_load_dwordx4 v[34:37], v214, s[18:19] offset:0
	global_load_dwordx4 v[38:41], v214, s[18:19] offset:1024
	global_load_dwordx4 v[42:45], v214, s[18:19] offset:2048
	global_load_dwordx4 v[46:49], v214, s[18:19] offset:3072
	s_add_u32 s18, s18, 0x1000
	s_addc_u32 s19, s19, 0
	global_load_dwordx4 v[50:53], v214, s[18:19] offset:0
	s_add_i32 s10, s4, 2
	s_mul_i32 s14, s10, 0x3200
	s_add_u32 s18, s20, s14
	s_addc_u32 s19, s21, 0
	global_load_dwordx4 v[54:57], v214, s[18:19] offset:0
	global_load_dwordx4 v[58:61], v214, s[18:19] offset:1024
	global_load_dwordx4 v[62:65], v214, s[18:19] offset:2048
	global_load_dwordx4 v[66:69], v214, s[18:19] offset:3072
	s_add_u32 s18, s18, 0x1000
	s_addc_u32 s19, s19, 0
	global_load_dwordx4 v[70:73], v214, s[18:19] offset:0
	global_load_dwordx4 v[74:77], v214, s[18:19] offset:1024
	global_load_dwordx4 v[78:81], v214, s[18:19] offset:2048
	global_load_dwordx4 v[82:85], v214, s[18:19] offset:3072
	s_add_u32 s18, s18, 0x1000
	s_addc_u32 s19, s19, 0
	global_load_dwordx4 v[86:89], v214, s[18:19] offset:0
	global_load_dwordx4 v[90:93], v214, s[18:19] offset:1024
	global_load_dwordx4 v[94:97], v214, s[18:19] offset:2048
	global_load_dwordx4 v[98:101], v214, s[18:19] offset:3072
	s_add_u32 s18, s18, 0x1000
	s_addc_u32 s19, s19, 0
	global_load_dwordx4 v[102:105], v214, s[18:19] offset:0
	s_add_i32 s10, s4, 4
	s_mul_i32 s14, s10, 0x3200
	s_add_u32 s18, s20, s14
	s_addc_u32 s19, s21, 0
	global_load_dwordx4 v[106:109], v214, s[18:19] offset:0
	global_load_dwordx4 v[110:113], v214, s[18:19] offset:1024
	global_load_dwordx4 v[114:117], v214, s[18:19] offset:2048
	global_load_dwordx4 v[118:121], v214, s[18:19] offset:3072
	s_add_u32 s18, s18, 0x1000
	s_addc_u32 s19, s19, 0
	global_load_dwordx4 v[122:125], v214, s[18:19] offset:0
	global_load_dwordx4 v[126:129], v214, s[18:19] offset:1024
	global_load_dwordx4 v[130:133], v214, s[18:19] offset:2048
	global_load_dwordx4 v[134:137], v214, s[18:19] offset:3072
	s_add_u32 s18, s18, 0x1000
	s_addc_u32 s19, s19, 0
	global_load_dwordx4 v[138:141], v214, s[18:19] offset:0
	global_load_dwordx4 v[142:145], v214, s[18:19] offset:1024
	global_load_dwordx4 v[146:149], v214, s[18:19] offset:2048
	global_load_dwordx4 v[150:153], v214, s[18:19] offset:3072
	s_add_u32 s18, s18, 0x1000
	s_addc_u32 s19, s19, 0
	global_load_dwordx4 v[154:157], v214, s[18:19] offset:0
	s_add_i32 s10, s4, 6
	s_mul_i32 s14, s10, 0x3200
	s_add_u32 s18, s20, s14
	s_addc_u32 s19, s21, 0
	global_load_dwordx4 v[158:161], v214, s[18:19] offset:0
	global_load_dwordx4 v[162:165], v214, s[18:19] offset:1024
	global_load_dwordx4 v[166:169], v214, s[18:19] offset:2048
	global_load_dwordx4 v[170:173], v214, s[18:19] offset:3072
	s_add_u32 s18, s18, 0x1000
	s_addc_u32 s19, s19, 0
	global_load_dwordx4 v[174:177], v214, s[18:19] offset:0
	global_load_dwordx4 v[178:181], v214, s[18:19] offset:1024
	global_load_dwordx4 v[182:185], v214, s[18:19] offset:2048
	global_load_dwordx4 v[186:189], v214, s[18:19] offset:3072
	s_add_u32 s18, s18, 0x1000
	s_addc_u32 s19, s19, 0
	global_load_dwordx4 v[190:193], v214, s[18:19] offset:0
	global_load_dwordx4 v[194:197], v214, s[18:19] offset:1024
	global_load_dwordx4 v[198:201], v214, s[18:19] offset:2048
	global_load_dwordx4 v[202:205], v214, s[18:19] offset:3072
	s_add_u32 s18, s18, 0x1000
	s_addc_u32 s19, s19, 0
	global_load_dwordx4 v[206:209], v214, s[18:19] offset:0
	s_mov_b32 s9, s4
.Lldr_loop:
	s_add_i32 s10, s9, 0
	s_waitcnt vmcnt(39)
	s_add_i32 s11, s5, s10
	s_add_i32 s12, s11, -7
	s_cmp_lt_i32 s12, 1
	s_cbranch_scc1 .Lldr_free_0
	v_mov_b32_e32 v216, 0x24170
.Lldr_poll_c0_0:
	ds_read_b32 v217, v216
	s_waitcnt lgkmcnt(0)
	v_cmp_gt_u32_e32 vcc, s12, v217
	s_cbranch_vccz .Lldr_pd_c0_0
	s_sleep 1
	s_branch .Lldr_poll_c0_0
.Lldr_pd_c0_0:
	v_mov_b32_e32 v216, 0x24174

.Lldr_pd_c0_1:
	v_mov_b32_e32 v216, 0x24178

.Lldr_pd_c0_2:
	v_mov_b32_e32 v216, 0x2417c

.Lldr_pd_c0_3:
.Lldr_free_0:
	s_and_b32 s13, s11, 7
	s_mul_i32 s13, s13, 0x3200
	v_add_u32_e32 v215, s13, v214
	ds_write_b128 v215, v[2:5] offset:0
	ds_write_b128 v215, v[6:9] offset:1024
	ds_write_b128 v215, v[10:13] offset:2048
	ds_write_b128 v215, v[14:17] offset:3072
	ds_write_b128 v215, v[18:21] offset:4096
	ds_write_b128 v215, v[22:25] offset:5120
	ds_write_b128 v215, v[26:29] offset:6144
	ds_write_b128 v215, v[30:33] offset:7168
	ds_write_b128 v215, v[34:37] offset:8192
	ds_write_b128 v215, v[38:41] offset:9216
	ds_write_b128 v215, v[42:45] offset:10240
	ds_write_b128 v215, v[46:49] offset:11264
	s_mov_b32 exec_hi, 0
	ds_write_b128 v215, v[50:53] offset:12288
	s_mov_b64 exec, -1
	s_waitcnt lgkmcnt(0)
	v_mov_b32_e32 v216, 0x24180
.Lldr_poll_l0:
	ds_read_b32 v217, v216
	s_waitcnt lgkmcnt(0)
	v_cmp_gt_u32_e32 vcc, s11, v217
	s_cbranch_vccz .Lldr_pd_l0
	s_sleep 1
	s_branch .Lldr_poll_l0
.Lldr_pd_l0:
	s_add_i32 s14, s11, 1
	v_mov_b32_e32 v217, s14
	s_mov_b64 exec, 1
	ds_write_b32 v216, v217
	s_mov_b64 exec, -1
	s_add_i32 s15, s10, 8
	s_min_i32 s15, s15, 127
	s_mul_i32 s14, s15, 0x3200
	s_add_u32 s18, s20, s14
	s_addc_u32 s19, s21, 0
	global_load_dwordx4 v[2:5], v214, s[18:19] offset:0
	global_load_dwordx4 v[6:9], v214, s[18:19] offset:1024
	global_load_dwordx4 v[10:13], v214, s[18:19] offset:2048
	global_load_dwordx4 v[14:17], v214, s[18:19] offset:3072
	s_add_u32 s18, s18, 0x1000
	s_addc_u32 s19, s19, 0
	global_load_dwordx4 v[18:21], v214, s[18:19] offset:0
	global_load_dwordx4 v[22:25], v214, s[18:19] offset:1024
	global_load_dwordx4 v[26:29], v214, s[18:19] offset:2048
	global_load_dwordx4 v[30:33], v214, s[18:19] offset:3072
	s_add_u32 s18, s18, 0x1000
	s_addc_u32 s19, s19, 0
	global_load_dwordx4 v[34:37], v214, s[18:19] offset:0
	global_load_dwordx4 v[38:41], v214, s[18:19] offset:1024
	global_load_dwordx4 v[42:45], v214, s[18:19] offset:2048
	global_load_dwordx4 v[46:49], v214, s[18:19] offset:3072
	s_add_u32 s18, s18, 0x1000
	s_addc_u32 s19, s19, 0
	global_load_dwordx4 v[50:53], v214, s[18:19] offset:0
	s_add_i32 s10, s9, 2
	s_waitcnt vmcnt(39)
	s_add_i32 s11, s5, s10
	s_add_i32 s12, s11, -7
	s_cmp_lt_i32 s12, 1
	s_cbranch_scc1 .Lldr_free_1
	v_mov_b32_e32 v216, 0x24170

.Lldr_pd_c1_3:
.Lldr_free_1:
	s_and_b32 s13, s11, 7
	s_mul_i32 s13, s13, 0x3200
	v_add_u32_e32 v215, s13, v214
	ds_write_b128 v215, v[54:57] offset:0
	ds_write_b128 v215, v[58:61] offset:1024
	ds_write_b128 v215, v[62:65] offset:2048
	ds_write_b128 v215, v[66:69] offset:3072
	ds_write_b128 v215, v[70:73] offset:4096
	ds_write_b128 v215, v[74:77] offset:5120
	ds_write_b128 v215, v[78:81] offset:6144
	ds_write_b128 v215, v[82:85] offset:7168
	ds_write_b128 v215, v[86:89] offset:8192
	ds_write_b128 v215, v[90:93] offset:9216
	ds_write_b128 v215, v[94:97] offset:10240
	ds_write_b128 v215, v[98:101] offset:11264
	s_mov_b32 exec_hi, 0
	ds_write_b128 v215, v[102:105] offset:12288
	s_mov_b64 exec, -1
	s_waitcnt lgkmcnt(0)
	v_mov_b32_e32 v216, 0x24180

.Lldr_pd_l1:
	s_add_i32 s14, s11, 1
	v_mov_b32_e32 v217, s14
	s_mov_b64 exec, 1
	ds_write_b32 v216, v217
	s_mov_b64 exec, -1
	s_add_i32 s15, s10, 8
	s_min_i32 s15, s15, 127
	s_mul_i32 s14, s15, 0x3200
	s_add_u32 s18, s20, s14
	s_addc_u32 s19, s21, 0
	global_load_dwordx4 v[54:57], v214, s[18:19] offset:0
	global_load_dwordx4 v[58:61], v214, s[18:19] offset:1024
	global_load_dwordx4 v[62:65], v214, s[18:19] offset:2048
	global_load_dwordx4 v[66:69], v214, s[18:19] offset:3072
	s_add_u32 s18, s18, 0x1000
	s_addc_u32 s19, s19, 0
	global_load_dwordx4 v[70:73], v214, s[18:19] offset:0
	global_load_dwordx4 v[74:77], v214, s[18:19] offset:1024
	global_load_dwordx4 v[78:81], v214, s[18:19] offset:2048
	global_load_dwordx4 v[82:85], v214, s[18:19] offset:3072
	s_add_u32 s18, s18, 0x1000
	s_addc_u32 s19, s19, 0
	global_load_dwordx4 v[86:89], v214, s[18:19] offset:0
	global_load_dwordx4 v[90:93], v214, s[18:19] offset:1024
	global_load_dwordx4 v[94:97], v214, s[18:19] offset:2048
	global_load_dwordx4 v[98:101], v214, s[18:19] offset:3072
	s_add_u32 s18, s18, 0x1000
	s_addc_u32 s19, s19, 0
	global_load_dwordx4 v[102:105], v214, s[18:19] offset:0
	s_add_i32 s10, s9, 4
	s_waitcnt vmcnt(39)
	s_add_i32 s11, s5, s10
	s_add_i32 s12, s11, -7
	s_cmp_lt_i32 s12, 1
	s_cbranch_scc1 .Lldr_free_2
	v_mov_b32_e32 v216, 0x24170

.Lldr_pd_c2_3:
.Lldr_free_2:
	s_and_b32 s13, s11, 7
	s_mul_i32 s13, s13, 0x3200
	v_add_u32_e32 v215, s13, v214
	ds_write_b128 v215, v[106:109] offset:0
	ds_write_b128 v215, v[110:113] offset:1024
	ds_write_b128 v215, v[114:117] offset:2048
	ds_write_b128 v215, v[118:121] offset:3072
	ds_write_b128 v215, v[122:125] offset:4096
	ds_write_b128 v215, v[126:129] offset:5120
	ds_write_b128 v215, v[130:133] offset:6144
	ds_write_b128 v215, v[134:137] offset:7168
	ds_write_b128 v215, v[138:141] offset:8192
	ds_write_b128 v215, v[142:145] offset:9216
	ds_write_b128 v215, v[146:149] offset:10240
	ds_write_b128 v215, v[150:153] offset:11264
	s_mov_b32 exec_hi, 0
	ds_write_b128 v215, v[154:157] offset:12288
	s_mov_b64 exec, -1
	s_waitcnt lgkmcnt(0)
	v_mov_b32_e32 v216, 0x24180

.Lldr_pd_l2:
	s_add_i32 s14, s11, 1
	v_mov_b32_e32 v217, s14
	s_mov_b64 exec, 1
	ds_write_b32 v216, v217
	s_mov_b64 exec, -1
	s_add_i32 s15, s10, 8
	s_min_i32 s15, s15, 127
	s_mul_i32 s14, s15, 0x3200
	s_add_u32 s18, s20, s14
	s_addc_u32 s19, s21, 0
	global_load_dwordx4 v[106:109], v214, s[18:19] offset:0
	global_load_dwordx4 v[110:113], v214, s[18:19] offset:1024
	global_load_dwordx4 v[114:117], v214, s[18:19] offset:2048
	global_load_dwordx4 v[118:121], v214, s[18:19] offset:3072
	s_add_u32 s18, s18, 0x1000
	s_addc_u32 s19, s19, 0
	global_load_dwordx4 v[122:125], v214, s[18:19] offset:0
	global_load_dwordx4 v[126:129], v214, s[18:19] offset:1024
	global_load_dwordx4 v[130:133], v214, s[18:19] offset:2048
	global_load_dwordx4 v[134:137], v214, s[18:19] offset:3072
	s_add_u32 s18, s18, 0x1000
	s_addc_u32 s19, s19, 0
	global_load_dwordx4 v[138:141], v214, s[18:19] offset:0
	global_load_dwordx4 v[142:145], v214, s[18:19] offset:1024
	global_load_dwordx4 v[146:149], v214, s[18:19] offset:2048
	global_load_dwordx4 v[150:153], v214, s[18:19] offset:3072
	s_add_u32 s18, s18, 0x1000
	s_addc_u32 s19, s19, 0
	global_load_dwordx4 v[154:157], v214, s[18:19] offset:0
	s_add_i32 s10, s9, 6
	s_waitcnt vmcnt(39)
	s_add_i32 s11, s5, s10
	s_add_i32 s12, s11, -7
	s_cmp_lt_i32 s12, 1
	s_cbranch_scc1 .Lldr_free_3
	v_mov_b32_e32 v216, 0x24170

.Lldr_pd_c3_3:
.Lldr_free_3:
	s_and_b32 s13, s11, 7
	s_mul_i32 s13, s13, 0x3200
	v_add_u32_e32 v215, s13, v214
	ds_write_b128 v215, v[158:161] offset:0
	ds_write_b128 v215, v[162:165] offset:1024
	ds_write_b128 v215, v[166:169] offset:2048
	ds_write_b128 v215, v[170:173] offset:3072
	ds_write_b128 v215, v[174:177] offset:4096
	ds_write_b128 v215, v[178:181] offset:5120
	ds_write_b128 v215, v[182:185] offset:6144
	ds_write_b128 v215, v[186:189] offset:7168
	ds_write_b128 v215, v[190:193] offset:8192
	ds_write_b128 v215, v[194:197] offset:9216
	ds_write_b128 v215, v[198:201] offset:10240
	ds_write_b128 v215, v[202:205] offset:11264
	s_mov_b32 exec_hi, 0
	ds_write_b128 v215, v[206:209] offset:12288
	s_mov_b64 exec, -1
	s_waitcnt lgkmcnt(0)
	v_mov_b32_e32 v216, 0x24180

.Lldr_pd_l3:
	s_add_i32 s14, s11, 1
	v_mov_b32_e32 v217, s14
	s_mov_b64 exec, 1
	ds_write_b32 v216, v217
	s_mov_b64 exec, -1
	s_add_i32 s15, s10, 8
	s_min_i32 s15, s15, 127
	s_mul_i32 s14, s15, 0x3200
	s_add_u32 s18, s20, s14
	s_addc_u32 s19, s21, 0
	global_load_dwordx4 v[158:161], v214, s[18:19] offset:0
	global_load_dwordx4 v[162:165], v214, s[18:19] offset:1024
	global_load_dwordx4 v[166:169], v214, s[18:19] offset:2048
	global_load_dwordx4 v[170:173], v214, s[18:19] offset:3072
	s_add_u32 s18, s18, 0x1000
	s_addc_u32 s19, s19, 0
	global_load_dwordx4 v[174:177], v214, s[18:19] offset:0
	global_load_dwordx4 v[178:181], v214, s[18:19] offset:1024
	global_load_dwordx4 v[182:185], v214, s[18:19] offset:2048
	global_load_dwordx4 v[186:189], v214, s[18:19] offset:3072
	s_add_u32 s18, s18, 0x1000
	s_addc_u32 s19, s19, 0
	global_load_dwordx4 v[190:193], v214, s[18:19] offset:0
	global_load_dwordx4 v[194:197], v214, s[18:19] offset:1024
	global_load_dwordx4 v[198:201], v214, s[18:19] offset:2048
	global_load_dwordx4 v[202:205], v214, s[18:19] offset:3072
	s_add_u32 s18, s18, 0x1000
	s_addc_u32 s19, s19, 0
	global_load_dwordx4 v[206:209], v214, s[18:19] offset:0
	s_add_i32 s9, s9, 8
	s_cmpk_lt_i32 s9, 128
	s_cbranch_scc1 .Lldr_loop
	s_waitcnt vmcnt(0)
	s_add_i32 s5, s5, 128
	s_add_i32 s50, s50, s51
	s_cmp_gt_i32 s50, 63
	s_cbranch_scc0 .Lldr_item

.LBB0_1181:
.LBB0_1182:
	s_cmp_lt_i32 s52, 1
	s_cbranch_scc1 .LBB0_1187
	s_cmp_eq_u32 s52, 1
	s_cbranch_scc1 .LBB0_1185
	s_cmp_eq_u32 s52, 2
	s_cselect_b32 s52, 22, 43
	s_cbranch_execz .LBB0_1186
	s_branch .LBB0_1187
.LBB0_1185:
.LBB0_1186:
	s_mov_b32 s52, 1

.LBB0_1188:
	s_and_b64 s[6:7], s[16:17], exec
	s_cselect_b32 s6, 1, 21
	s_and_b64 s[4:5], s[4:5], exec
	s_cselect_b32 s44, s6, s25
	s_add_i32 s4, s83, -6
	s_cmp_lt_u32 s4, 2
	s_cselect_b64 s[4:5], -1, 0
	s_or_b64 s[20:21], s[4:5], s[0:1]
	s_add_u32 s45, s26, 0x29800000
	s_addc_u32 s46, s27, 0
	s_add_u32 s18, s26, 0x13200000
	v_readlane_b32 s0, v255, 23
	s_addc_u32 s19, s27, 0
	v_readlane_b32 s14, v255, 37
	v_readlane_b32 s15, v255, 38
	s_add_u32 s30, s14, 0x8200000
	s_addc_u32 s31, s15, 0
	s_add_u32 s47, s14, 0x8300000
	s_addc_u32 s48, s15, 0
	s_add_u32 s49, s26, 0x33a00000
	s_addc_u32 s50, s27, 0
	s_add_u32 s51, s26, 0x34b00000
	s_addc_u32 s52, s27, 0
	s_waitcnt vmcnt(38)
	v_and_b32_e32 v4, 31, v1
	v_readlane_b32 s8, v255, 31
	s_add_u32 s34, s14, 0x8500000
	v_lshlrev_b32_e32 v2, 1, v4
	v_mov_b32_e32 v3, 0
	s_waitcnt vmcnt(5)
	v_ashrrev_i32_e32 v134, 5, v1
	v_readlane_b32 s1, v255, 24
	s_addc_u32 s35, s15, 0
	s_add_i32 s8, 0, 0x24194
	s_mov_b32 s23, 0
	v_cmp_eq_u32_e64 s[72:73], 0, v1
	v_cmp_eq_u32_e64 s[74:75], 0, v4
	v_lshlrev_b32_e32 v120, 3, v4
	v_mov_b32_e32 v121, v3
	v_add_u32_e32 v135, 2, v134
	s_mov_b64 s[0:1], -1
	v_mov_b32_e32 v136, s8
	s_add_i32 s53, 0, 0x241a4
	s_add_i32 s54, 0, 0x241b4
	v_lshlrev_b32_e32 v122, 2, v2
	s_movk_i32 s55, 0x1000
	s_mov_b64 s[36:37], 0x400
	s_add_i32 s64, 0, 0x241a0
	s_movk_i32 s65, 0xc00
	s_mov_b64 s[38:39], 0x1000
	s_mov_b64 s[40:41], -1
	v_readlane_b32 s2, v255, 25
	v_readlane_b32 s3, v255, 26
	v_readlane_b32 s4, v255, 27
	v_readlane_b32 s5, v255, 28
	v_readlane_b32 s6, v255, 29
	v_readlane_b32 s7, v255, 30
	v_readlane_b32 s9, v255, 32
	v_readlane_b32 s10, v255, 33
	v_readlane_b32 s11, v255, 34
	v_readlane_b32 s12, v255, 35
	v_readlane_b32 s13, v255, 36
	s_branch .LBB0_1193

.LBB0_1206:
.LBB0_1207:
	s_ashr_i32 s22, s10, 2
	s_and_b32 s68, s10, 3
	s_mul_i32 s12, s22, 0x1800
	s_add_u32 s14, s45, s12
	s_addc_u32 s15, s46, 0
	s_add_u32 s42, s14, 0x1000
	s_addc_u32 s43, s15, 0
	v_lshlrev_b32_e32 v128, 2, v134
	v_mov_b32_e32 v129, 0
	s_lshl_b32 s12, s68, 6
	v_add_u32_e32 v117, s12, v128
	v_lshl_add_u32 v118, v134, 8, v122
	global_load_dwordx2 v[4:5], v122, s[14:15] offset:0
	global_load_dwordx2 v[6:7], v122, s[14:15] offset:256
	global_load_dwordx2 v[8:9], v122, s[14:15] offset:512
	global_load_dwordx2 v[10:11], v122, s[14:15] offset:768
	global_load_dwordx2 v[12:13], v122, s[14:15] offset:1024
	global_load_dwordx2 v[14:15], v122, s[14:15] offset:1536
	global_load_dwordx2 v[16:17], v122, s[14:15] offset:1792
	global_load_dwordx2 v[18:19], v122, s[14:15] offset:2048
	global_load_dwordx2 v[20:21], v122, s[14:15] offset:2304
	global_load_dwordx2 v[22:23], v122, s[14:15] offset:2560
	global_load_dwordx2 v[24:25], v122, s[14:15] offset:3072
	global_load_dwordx2 v[26:27], v122, s[14:15] offset:3328
	global_load_dwordx2 v[28:29], v122, s[14:15] offset:3584
	global_load_dwordx2 v[30:31], v122, s[14:15] offset:3840
	global_load_dwordx2 v[32:33], v122, s[42:43] offset:0
	global_load_dwordx2 v[34:35], v122, s[42:43] offset:512
	global_load_dwordx2 v[36:37], v122, s[42:43] offset:768
	global_load_dwordx2 v[38:39], v122, s[42:43] offset:1024
	global_load_dwordx2 v[40:41], v122, s[42:43] offset:1280
	global_load_dwordx2 v[42:43], v122, s[42:43] offset:1536
	s_lshl_b32 s12, s22, 14
	s_lshl_b32 s13, s68, 12
	s_add_i32 s22, s12, s13
	s_add_u32 s12, s62, s22
	s_addc_u32 s13, s63, 0
	global_load_dwordx2 v[76:77], v118, s[12:13] offset:0
	global_load_dwordx2 v[78:79], v118, s[12:13] offset:512
	global_load_dwordx2 v[80:81], v118, s[12:13] offset:1024
	global_load_dwordx2 v[82:83], v118, s[12:13] offset:1536
	global_load_dwordx2 v[84:85], v118, s[12:13] offset:2048
	global_load_dwordx2 v[86:87], v118, s[12:13] offset:2560
	global_load_dwordx2 v[88:89], v118, s[12:13] offset:3072
	global_load_dwordx2 v[90:91], v118, s[12:13] offset:3584
	global_load_dword v44, v117, s[14:15] offset:1280
	global_load_dword v45, v117, s[14:15] offset:1288
	global_load_dword v46, v117, s[14:15] offset:1296
	global_load_dword v47, v117, s[14:15] offset:1304
	global_load_dword v48, v117, s[14:15] offset:1312
	global_load_dword v49, v117, s[14:15] offset:1320
	global_load_dword v50, v117, s[14:15] offset:1328
	global_load_dword v51, v117, s[14:15] offset:1336
	global_load_dword v52, v117, s[14:15] offset:2816
	global_load_dword v53, v117, s[14:15] offset:2824
	global_load_dword v54, v117, s[14:15] offset:2832
	global_load_dword v55, v117, s[14:15] offset:2840
	global_load_dword v56, v117, s[14:15] offset:2848
	global_load_dword v57, v117, s[14:15] offset:2856
	global_load_dword v58, v117, s[14:15] offset:2864
	global_load_dword v59, v117, s[14:15] offset:2872
	global_load_dword v60, v117, s[42:43] offset:256
	global_load_dword v61, v117, s[42:43] offset:264
	global_load_dword v62, v117, s[42:43] offset:272
	global_load_dword v63, v117, s[42:43] offset:280
	global_load_dword v64, v117, s[42:43] offset:288
	global_load_dword v65, v117, s[42:43] offset:296
	global_load_dword v66, v117, s[42:43] offset:304
	global_load_dword v67, v117, s[42:43] offset:312
	global_load_dword v68, v117, s[42:43] offset:1792
	global_load_dword v69, v117, s[42:43] offset:1800
	global_load_dword v70, v117, s[42:43] offset:1808
	global_load_dword v71, v117, s[42:43] offset:1816
	global_load_dword v72, v117, s[42:43] offset:1824
	global_load_dword v73, v117, s[42:43] offset:1832
	global_load_dword v74, v117, s[42:43] offset:1840
	global_load_dword v75, v117, s[42:43] offset:1848
	s_ashr_i32 s10, s10, 2
	s_lshr_b32 s11, s10, 3
	s_lshl_b32 s11, s11, 13
	s_and_b32 s10, s10, 7
	s_lshl_b32 s10, s10, 8
	s_add_i32 s11, s11, s10
	s_lshl_b32 s10, s68, 6
	s_add_i32 s11, s11, s10
	s_add_u32 s10, s26, 0x2bf00000
	s_addc_u32 s68, s27, 0
	s_add_u32 s10, s10, 0x2000000
	s_addc_u32 s68, s68, 0
	s_add_u32 s10, s10, s11
	s_addc_u32 s11, s68, 0
	v_lshl_add_u64 v[124:125], s[10:11], 0, v[128:129]
	v_add_co_u32_e32 v126, vcc, 0x1000, v124
	s_nop 1
	v_addc_co_u32_e32 v127, vcc, 0, v125, vcc
	s_add_u32 s10, s34, s22
	s_addc_u32 s11, s35, 0
	s_waitcnt vmcnt(0)
	v_mul_f32_e32 v92, v76, v4
	v_mul_f32_e32 v93, v78, v4
	v_mul_f32_e32 v94, v80, v4
	v_mul_f32_e32 v95, v82, v4
	v_mul_f32_e32 v96, v84, v4
	v_mul_f32_e32 v97, v86, v4
	v_mul_f32_e32 v98, v88, v4
	v_mul_f32_e32 v99, v90, v4
	v_fmac_f32_e32 v92, v77, v5
	v_fmac_f32_e32 v93, v79, v5
	v_fmac_f32_e32 v94, v81, v5
	v_fmac_f32_e32 v95, v83, v5
	v_fmac_f32_e32 v96, v85, v5
	v_fmac_f32_e32 v97, v87, v5
	v_fmac_f32_e32 v98, v89, v5
	v_fmac_f32_e32 v99, v91, v5
	v_add_f32_dpp v92, v92, v92 quad_perm:[1,0,3,2] row_mask:0xf bank_mask:0xf bound_ctrl:1
	v_add_f32_dpp v93, v93, v93 quad_perm:[1,0,3,2] row_mask:0xf bank_mask:0xf bound_ctrl:1
	v_add_f32_dpp v94, v94, v94 quad_perm:[1,0,3,2] row_mask:0xf bank_mask:0xf bound_ctrl:1
	v_add_f32_dpp v95, v95, v95 quad_perm:[1,0,3,2] row_mask:0xf bank_mask:0xf bound_ctrl:1
	v_add_f32_dpp v96, v96, v96 quad_perm:[1,0,3,2] row_mask:0xf bank_mask:0xf bound_ctrl:1
	v_add_f32_dpp v97, v97, v97 quad_perm:[1,0,3,2] row_mask:0xf bank_mask:0xf bound_ctrl:1
	v_add_f32_dpp v98, v98, v98 quad_perm:[1,0,3,2] row_mask:0xf bank_mask:0xf bound_ctrl:1
	v_add_f32_dpp v99, v99, v99 quad_perm:[1,0,3,2] row_mask:0xf bank_mask:0xf bound_ctrl:1
	v_add_f32_dpp v92, v92, v92 quad_perm:[2,3,0,1] row_mask:0xf bank_mask:0xf bound_ctrl:1
	v_add_f32_dpp v93, v93, v93 quad_perm:[2,3,0,1] row_mask:0xf bank_mask:0xf bound_ctrl:1
	v_add_f32_dpp v94, v94, v94 quad_perm:[2,3,0,1] row_mask:0xf bank_mask:0xf bound_ctrl:1
	v_add_f32_dpp v95, v95, v95 quad_perm:[2,3,0,1] row_mask:0xf bank_mask:0xf bound_ctrl:1
	v_add_f32_dpp v96, v96, v96 quad_perm:[2,3,0,1] row_mask:0xf bank_mask:0xf bound_ctrl:1
	v_add_f32_dpp v97, v97, v97 quad_perm:[2,3,0,1] row_mask:0xf bank_mask:0xf bound_ctrl:1
	v_add_f32_dpp v98, v98, v98 quad_perm:[2,3,0,1] row_mask:0xf bank_mask:0xf bound_ctrl:1
	v_add_f32_dpp v99, v99, v99 quad_perm:[2,3,0,1] row_mask:0xf bank_mask:0xf bound_ctrl:1
	v_add_f32_dpp v92, v92, v92 row_half_mirror row_mask:0xf bank_mask:0xf bound_ctrl:1
	v_add_f32_dpp v93, v93, v93 row_half_mirror row_mask:0xf bank_mask:0xf bound_ctrl:1
	v_add_f32_dpp v94, v94, v94 row_half_mirror row_mask:0xf bank_mask:0xf bound_ctrl:1
	v_add_f32_dpp v95, v95, v95 row_half_mirror row_mask:0xf bank_mask:0xf bound_ctrl:1
	v_add_f32_dpp v96, v96, v96 row_half_mirror row_mask:0xf bank_mask:0xf bound_ctrl:1
	v_add_f32_dpp v97, v97, v97 row_half_mirror row_mask:0xf bank_mask:0xf bound_ctrl:1
	v_add_f32_dpp v98, v98, v98 row_half_mirror row_mask:0xf bank_mask:0xf bound_ctrl:1
	v_add_f32_dpp v99, v99, v99 row_half_mirror row_mask:0xf bank_mask:0xf bound_ctrl:1
	v_add_f32_dpp v92, v92, v92 row_mirror row_mask:0xf bank_mask:0xf bound_ctrl:1
	v_add_f32_dpp v93, v93, v93 row_mirror row_mask:0xf bank_mask:0xf bound_ctrl:1
	v_add_f32_dpp v94, v94, v94 row_mirror row_mask:0xf bank_mask:0xf bound_ctrl:1
	v_add_f32_dpp v95, v95, v95 row_mirror row_mask:0xf bank_mask:0xf bound_ctrl:1
	v_add_f32_dpp v96, v96, v96 row_mirror row_mask:0xf bank_mask:0xf bound_ctrl:1
	v_add_f32_dpp v97, v97, v97 row_mirror row_mask:0xf bank_mask:0xf bound_ctrl:1
	v_add_f32_dpp v98, v98, v98 row_mirror row_mask:0xf bank_mask:0xf bound_ctrl:1
	v_add_f32_dpp v99, v99, v99 row_mirror row_mask:0xf bank_mask:0xf bound_ctrl:1
	v_mov_b32_e32 v100, v92
	v_mov_b32_e32 v101, v93
	v_mov_b32_e32 v102, v94
	v_mov_b32_e32 v103, v95
	v_mov_b32_e32 v104, v96
	v_mov_b32_e32 v105, v97
	v_mov_b32_e32 v106, v98
	v_mov_b32_e32 v107, v99
	v_permlane16_swap_b32_e32 v92, v100
	v_permlane16_swap_b32_e32 v93, v101
	v_permlane16_swap_b32_e32 v94, v102
	v_permlane16_swap_b32_e32 v95, v103
	v_permlane16_swap_b32_e32 v96, v104
	v_permlane16_swap_b32_e32 v97, v105
	v_permlane16_swap_b32_e32 v98, v106
	v_permlane16_swap_b32_e32 v99, v107
	v_add_f32_e32 v92, v92, v100
	v_add_f32_e32 v93, v93, v101
	v_add_f32_e32 v94, v94, v102
	v_add_f32_e32 v95, v95, v103
	v_add_f32_e32 v96, v96, v104
	v_add_f32_e32 v97, v97, v105
	v_add_f32_e32 v98, v98, v106
	v_add_f32_e32 v99, v99, v107
	v_pk_mul_f32 v[76:77], v[76:77], v[6:7]
	v_pk_mul_f32 v[78:79], v[78:79], v[6:7]
	v_pk_mul_f32 v[80:81], v[80:81], v[6:7]
	v_pk_mul_f32 v[82:83], v[82:83], v[6:7]
	v_pk_mul_f32 v[84:85], v[84:85], v[6:7]
	v_pk_mul_f32 v[86:87], v[86:87], v[6:7]
	v_pk_mul_f32 v[88:89], v[88:89], v[6:7]
	v_pk_mul_f32 v[90:91], v[90:91], v[6:7]
	v_fmac_f32_e32 v76, v92, v8
	v_fmac_f32_e32 v77, v92, v9
	v_fmac_f32_e32 v78, v93, v8
	v_fmac_f32_e32 v79, v93, v9
	v_fmac_f32_e32 v80, v94, v8
	v_fmac_f32_e32 v81, v94, v9
	v_fmac_f32_e32 v82, v95, v8
	v_fmac_f32_e32 v83, v95, v9
	v_fmac_f32_e32 v84, v96, v8
	v_fmac_f32_e32 v85, v96, v9
	v_fmac_f32_e32 v86, v97, v8
	v_fmac_f32_e32 v87, v97, v9
	v_fmac_f32_e32 v88, v98, v8
	v_fmac_f32_e32 v89, v98, v9
	v_fmac_f32_e32 v90, v99, v8
	v_fmac_f32_e32 v91, v99, v9
	v_fmac_f32_e32 v76, v44, v10
	v_fmac_f32_e32 v77, v44, v11
	v_fmac_f32_e32 v78, v45, v10
	v_fmac_f32_e32 v79, v45, v11
	v_fmac_f32_e32 v80, v46, v10
	v_fmac_f32_e32 v81, v46, v11
	v_fmac_f32_e32 v82, v47, v10
	v_fmac_f32_e32 v83, v47, v11
	v_fmac_f32_e32 v84, v48, v10
	v_fmac_f32_e32 v85, v48, v11
	v_fmac_f32_e32 v86, v49, v10
	v_fmac_f32_e32 v87, v49, v11
	v_fmac_f32_e32 v88, v50, v10
	v_fmac_f32_e32 v89, v50, v11
	v_fmac_f32_e32 v90, v51, v10
	v_fmac_f32_e32 v91, v51, v11
	v_mul_f32_e32 v92, v76, v12
	v_mul_f32_e32 v93, v78, v12
	v_mul_f32_e32 v94, v80, v12
	v_mul_f32_e32 v95, v82, v12
	v_mul_f32_e32 v96, v84, v12
	v_mul_f32_e32 v97, v86, v12
	v_mul_f32_e32 v98, v88, v12
	v_mul_f32_e32 v99, v90, v12
	v_fmac_f32_e32 v92, v77, v13
	v_fmac_f32_e32 v93, v79, v13
	v_fmac_f32_e32 v94, v81, v13
	v_fmac_f32_e32 v95, v83, v13
	v_fmac_f32_e32 v96, v85, v13
	v_fmac_f32_e32 v97, v87, v13
	v_fmac_f32_e32 v98, v89, v13
	v_fmac_f32_e32 v99, v91, v13
	v_add_f32_dpp v92, v92, v92 quad_perm:[1,0,3,2] row_mask:0xf bank_mask:0xf bound_ctrl:1
	v_add_f32_dpp v93, v93, v93 quad_perm:[1,0,3,2] row_mask:0xf bank_mask:0xf bound_ctrl:1
	v_add_f32_dpp v94, v94, v94 quad_perm:[1,0,3,2] row_mask:0xf bank_mask:0xf bound_ctrl:1
	v_add_f32_dpp v95, v95, v95 quad_perm:[1,0,3,2] row_mask:0xf bank_mask:0xf bound_ctrl:1
	v_add_f32_dpp v96, v96, v96 quad_perm:[1,0,3,2] row_mask:0xf bank_mask:0xf bound_ctrl:1
	v_add_f32_dpp v97, v97, v97 quad_perm:[1,0,3,2] row_mask:0xf bank_mask:0xf bound_ctrl:1
	v_add_f32_dpp v98, v98, v98 quad_perm:[1,0,3,2] row_mask:0xf bank_mask:0xf bound_ctrl:1
	v_add_f32_dpp v99, v99, v99 quad_perm:[1,0,3,2] row_mask:0xf bank_mask:0xf bound_ctrl:1
	v_add_f32_dpp v92, v92, v92 quad_perm:[2,3,0,1] row_mask:0xf bank_mask:0xf bound_ctrl:1
	v_add_f32_dpp v93, v93, v93 quad_perm:[2,3,0,1] row_mask:0xf bank_mask:0xf bound_ctrl:1
	v_add_f32_dpp v94, v94, v94 quad_perm:[2,3,0,1] row_mask:0xf bank_mask:0xf bound_ctrl:1
	v_add_f32_dpp v95, v95, v95 quad_perm:[2,3,0,1] row_mask:0xf bank_mask:0xf bound_ctrl:1
	v_add_f32_dpp v96, v96, v96 quad_perm:[2,3,0,1] row_mask:0xf bank_mask:0xf bound_ctrl:1
	v_add_f32_dpp v97, v97, v97 quad_perm:[2,3,0,1] row_mask:0xf bank_mask:0xf bound_ctrl:1
	v_add_f32_dpp v98, v98, v98 quad_perm:[2,3,0,1] row_mask:0xf bank_mask:0xf bound_ctrl:1
	v_add_f32_dpp v99, v99, v99 quad_perm:[2,3,0,1] row_mask:0xf bank_mask:0xf bound_ctrl:1
	v_add_f32_dpp v92, v92, v92 row_half_mirror row_mask:0xf bank_mask:0xf bound_ctrl:1
	v_add_f32_dpp v93, v93, v93 row_half_mirror row_mask:0xf bank_mask:0xf bound_ctrl:1
	v_add_f32_dpp v94, v94, v94 row_half_mirror row_mask:0xf bank_mask:0xf bound_ctrl:1
	v_add_f32_dpp v95, v95, v95 row_half_mirror row_mask:0xf bank_mask:0xf bound_ctrl:1
	v_add_f32_dpp v96, v96, v96 row_half_mirror row_mask:0xf bank_mask:0xf bound_ctrl:1
	v_add_f32_dpp v97, v97, v97 row_half_mirror row_mask:0xf bank_mask:0xf bound_ctrl:1
	v_add_f32_dpp v98, v98, v98 row_half_mirror row_mask:0xf bank_mask:0xf bound_ctrl:1
	v_add_f32_dpp v99, v99, v99 row_half_mirror row_mask:0xf bank_mask:0xf bound_ctrl:1
	v_add_f32_dpp v92, v92, v92 row_mirror row_mask:0xf bank_mask:0xf bound_ctrl:1
	v_add_f32_dpp v93, v93, v93 row_mirror row_mask:0xf bank_mask:0xf bound_ctrl:1
	v_add_f32_dpp v94, v94, v94 row_mirror row_mask:0xf bank_mask:0xf bound_ctrl:1
	v_add_f32_dpp v95, v95, v95 row_mirror row_mask:0xf bank_mask:0xf bound_ctrl:1
	v_add_f32_dpp v96, v96, v96 row_mirror row_mask:0xf bank_mask:0xf bound_ctrl:1
	v_add_f32_dpp v97, v97, v97 row_mirror row_mask:0xf bank_mask:0xf bound_ctrl:1
	v_add_f32_dpp v98, v98, v98 row_mirror row_mask:0xf bank_mask:0xf bound_ctrl:1
	v_add_f32_dpp v99, v99, v99 row_mirror row_mask:0xf bank_mask:0xf bound_ctrl:1
	v_mov_b32_e32 v100, v92
	v_mov_b32_e32 v101, v93
	v_mov_b32_e32 v102, v94
	v_mov_b32_e32 v103, v95
	v_mov_b32_e32 v104, v96
	v_mov_b32_e32 v105, v97
	v_mov_b32_e32 v106, v98
	v_mov_b32_e32 v107, v99
	v_permlane16_swap_b32_e32 v92, v100
	v_permlane16_swap_b32_e32 v93, v101
	v_permlane16_swap_b32_e32 v94, v102
	v_permlane16_swap_b32_e32 v95, v103
	v_permlane16_swap_b32_e32 v96, v104
	v_permlane16_swap_b32_e32 v97, v105
	v_permlane16_swap_b32_e32 v98, v106
	v_permlane16_swap_b32_e32 v99, v107
	v_add_f32_e32 v92, v92, v100
	v_add_f32_e32 v93, v93, v101
	v_add_f32_e32 v94, v94, v102
	v_add_f32_e32 v95, v95, v103
	v_add_f32_e32 v96, v96, v104
	v_add_f32_e32 v97, v97, v105
	v_add_f32_e32 v98, v98, v106
	v_add_f32_e32 v99, v99, v107
	s_mov_b64 exec, s[74:75]
	global_store_dword v[124:125], v92, off offset:0
	global_store_dword v[124:125], v93, off offset:8
	global_store_dword v[124:125], v94, off offset:16
	global_store_dword v[124:125], v95, off offset:24
	global_store_dword v[124:125], v96, off offset:32
	global_store_dword v[124:125], v97, off offset:40
	global_store_dword v[124:125], v98, off offset:48
	global_store_dword v[124:125], v99, off offset:56
	s_mov_b64 exec, -1
	v_mul_f32_e32 v92, v76, v14
	v_mul_f32_e32 v93, v78, v14
	v_mul_f32_e32 v94, v80, v14
	v_mul_f32_e32 v95, v82, v14
	v_mul_f32_e32 v96, v84, v14
	v_mul_f32_e32 v97, v86, v14
	v_mul_f32_e32 v98, v88, v14
	v_mul_f32_e32 v99, v90, v14
	v_fmac_f32_e32 v92, v77, v15
	v_fmac_f32_e32 v93, v79, v15
	v_fmac_f32_e32 v94, v81, v15
	v_fmac_f32_e32 v95, v83, v15
	v_fmac_f32_e32 v96, v85, v15
	v_fmac_f32_e32 v97, v87, v15
	v_fmac_f32_e32 v98, v89, v15
	v_fmac_f32_e32 v99, v91, v15
	v_add_f32_dpp v92, v92, v92 quad_perm:[1,0,3,2] row_mask:0xf bank_mask:0xf bound_ctrl:1
	v_add_f32_dpp v93, v93, v93 quad_perm:[1,0,3,2] row_mask:0xf bank_mask:0xf bound_ctrl:1
	v_add_f32_dpp v94, v94, v94 quad_perm:[1,0,3,2] row_mask:0xf bank_mask:0xf bound_ctrl:1
	v_add_f32_dpp v95, v95, v95 quad_perm:[1,0,3,2] row_mask:0xf bank_mask:0xf bound_ctrl:1
	v_add_f32_dpp v96, v96, v96 quad_perm:[1,0,3,2] row_mask:0xf bank_mask:0xf bound_ctrl:1
	v_add_f32_dpp v97, v97, v97 quad_perm:[1,0,3,2] row_mask:0xf bank_mask:0xf bound_ctrl:1
	v_add_f32_dpp v98, v98, v98 quad_perm:[1,0,3,2] row_mask:0xf bank_mask:0xf bound_ctrl:1
	v_add_f32_dpp v99, v99, v99 quad_perm:[1,0,3,2] row_mask:0xf bank_mask:0xf bound_ctrl:1
	v_add_f32_dpp v92, v92, v92 quad_perm:[2,3,0,1] row_mask:0xf bank_mask:0xf bound_ctrl:1
	v_add_f32_dpp v93, v93, v93 quad_perm:[2,3,0,1] row_mask:0xf bank_mask:0xf bound_ctrl:1
	v_add_f32_dpp v94, v94, v94 quad_perm:[2,3,0,1] row_mask:0xf bank_mask:0xf bound_ctrl:1
	v_add_f32_dpp v95, v95, v95 quad_perm:[2,3,0,1] row_mask:0xf bank_mask:0xf bound_ctrl:1
	v_add_f32_dpp v96, v96, v96 quad_perm:[2,3,0,1] row_mask:0xf bank_mask:0xf bound_ctrl:1
	v_add_f32_dpp v97, v97, v97 quad_perm:[2,3,0,1] row_mask:0xf bank_mask:0xf bound_ctrl:1
	v_add_f32_dpp v98, v98, v98 quad_perm:[2,3,0,1] row_mask:0xf bank_mask:0xf bound_ctrl:1
	v_add_f32_dpp v99, v99, v99 quad_perm:[2,3,0,1] row_mask:0xf bank_mask:0xf bound_ctrl:1
	v_add_f32_dpp v92, v92, v92 row_half_mirror row_mask:0xf bank_mask:0xf bound_ctrl:1
	v_add_f32_dpp v93, v93, v93 row_half_mirror row_mask:0xf bank_mask:0xf bound_ctrl:1
	v_add_f32_dpp v94, v94, v94 row_half_mirror row_mask:0xf bank_mask:0xf bound_ctrl:1
	v_add_f32_dpp v95, v95, v95 row_half_mirror row_mask:0xf bank_mask:0xf bound_ctrl:1
	v_add_f32_dpp v96, v96, v96 row_half_mirror row_mask:0xf bank_mask:0xf bound_ctrl:1
	v_add_f32_dpp v97, v97, v97 row_half_mirror row_mask:0xf bank_mask:0xf bound_ctrl:1
	v_add_f32_dpp v98, v98, v98 row_half_mirror row_mask:0xf bank_mask:0xf bound_ctrl:1
	v_add_f32_dpp v99, v99, v99 row_half_mirror row_mask:0xf bank_mask:0xf bound_ctrl:1
	v_add_f32_dpp v92, v92, v92 row_mirror row_mask:0xf bank_mask:0xf bound_ctrl:1
	v_add_f32_dpp v93, v93, v93 row_mirror row_mask:0xf bank_mask:0xf bound_ctrl:1
	v_add_f32_dpp v94, v94, v94 row_mirror row_mask:0xf bank_mask:0xf bound_ctrl:1
	v_add_f32_dpp v95, v95, v95 row_mirror row_mask:0xf bank_mask:0xf bound_ctrl:1
	v_add_f32_dpp v96, v96, v96 row_mirror row_mask:0xf bank_mask:0xf bound_ctrl:1
	v_add_f32_dpp v97, v97, v97 row_mirror row_mask:0xf bank_mask:0xf bound_ctrl:1
	v_add_f32_dpp v98, v98, v98 row_mirror row_mask:0xf bank_mask:0xf bound_ctrl:1
	v_add_f32_dpp v99, v99, v99 row_mirror row_mask:0xf bank_mask:0xf bound_ctrl:1
	v_mov_b32_e32 v100, v92
	v_mov_b32_e32 v101, v93
	v_mov_b32_e32 v102, v94
	v_mov_b32_e32 v103, v95
	v_mov_b32_e32 v104, v96
	v_mov_b32_e32 v105, v97
	v_mov_b32_e32 v106, v98
	v_mov_b32_e32 v107, v99
	v_permlane16_swap_b32_e32 v92, v100
	v_permlane16_swap_b32_e32 v93, v101
	v_permlane16_swap_b32_e32 v94, v102
	v_permlane16_swap_b32_e32 v95, v103
	v_permlane16_swap_b32_e32 v96, v104
	v_permlane16_swap_b32_e32 v97, v105
	v_permlane16_swap_b32_e32 v98, v106
	v_permlane16_swap_b32_e32 v99, v107
	v_add_f32_e32 v92, v92, v100
	v_add_f32_e32 v93, v93, v101
	v_add_f32_e32 v94, v94, v102
	v_add_f32_e32 v95, v95, v103
	v_add_f32_e32 v96, v96, v104
	v_add_f32_e32 v97, v97, v105
	v_add_f32_e32 v98, v98, v106
	v_add_f32_e32 v99, v99, v107
	v_pk_mul_f32 v[76:77], v[76:77], v[16:17]
	v_pk_mul_f32 v[78:79], v[78:79], v[16:17]
	v_pk_mul_f32 v[80:81], v[80:81], v[16:17]
	v_pk_mul_f32 v[82:83], v[82:83], v[16:17]
	v_pk_mul_f32 v[84:85], v[84:85], v[16:17]
	v_pk_mul_f32 v[86:87], v[86:87], v[16:17]
	v_pk_mul_f32 v[88:89], v[88:89], v[16:17]
	v_pk_mul_f32 v[90:91], v[90:91], v[16:17]
	v_fmac_f32_e32 v76, v92, v18
	v_fmac_f32_e32 v77, v92, v19
	v_fmac_f32_e32 v78, v93, v18
	v_fmac_f32_e32 v79, v93, v19
	v_fmac_f32_e32 v80, v94, v18
	v_fmac_f32_e32 v81, v94, v19
	v_fmac_f32_e32 v82, v95, v18
	v_fmac_f32_e32 v83, v95, v19
	v_fmac_f32_e32 v84, v96, v18
	v_fmac_f32_e32 v85, v96, v19
	v_fmac_f32_e32 v86, v97, v18
	v_fmac_f32_e32 v87, v97, v19
	v_fmac_f32_e32 v88, v98, v18
	v_fmac_f32_e32 v89, v98, v19
	v_fmac_f32_e32 v90, v99, v18
	v_fmac_f32_e32 v91, v99, v19
	v_fmac_f32_e32 v76, v52, v20
	v_fmac_f32_e32 v77, v52, v21
	v_fmac_f32_e32 v78, v53, v20
	v_fmac_f32_e32 v79, v53, v21
	v_fmac_f32_e32 v80, v54, v20
	v_fmac_f32_e32 v81, v54, v21
	v_fmac_f32_e32 v82, v55, v20
	v_fmac_f32_e32 v83, v55, v21
	v_fmac_f32_e32 v84, v56, v20
	v_fmac_f32_e32 v85, v56, v21
	v_fmac_f32_e32 v86, v57, v20
	v_fmac_f32_e32 v87, v57, v21
	v_fmac_f32_e32 v88, v58, v20
	v_fmac_f32_e32 v89, v58, v21
	v_fmac_f32_e32 v90, v59, v20
	v_fmac_f32_e32 v91, v59, v21
	v_mul_f32_e32 v92, v76, v22
	v_mul_f32_e32 v93, v78, v22
	v_mul_f32_e32 v94, v80, v22
	v_mul_f32_e32 v95, v82, v22
	v_mul_f32_e32 v96, v84, v22
	v_mul_f32_e32 v97, v86, v22
	v_mul_f32_e32 v98, v88, v22
	v_mul_f32_e32 v99, v90, v22
	v_fmac_f32_e32 v92, v77, v23
	v_fmac_f32_e32 v93, v79, v23
	v_fmac_f32_e32 v94, v81, v23
	v_fmac_f32_e32 v95, v83, v23
	v_fmac_f32_e32 v96, v85, v23
	v_fmac_f32_e32 v97, v87, v23
	v_fmac_f32_e32 v98, v89, v23
	v_fmac_f32_e32 v99, v91, v23
	v_add_f32_dpp v92, v92, v92 quad_perm:[1,0,3,2] row_mask:0xf bank_mask:0xf bound_ctrl:1
	v_add_f32_dpp v93, v93, v93 quad_perm:[1,0,3,2] row_mask:0xf bank_mask:0xf bound_ctrl:1
	v_add_f32_dpp v94, v94, v94 quad_perm:[1,0,3,2] row_mask:0xf bank_mask:0xf bound_ctrl:1
	v_add_f32_dpp v95, v95, v95 quad_perm:[1,0,3,2] row_mask:0xf bank_mask:0xf bound_ctrl:1
	v_add_f32_dpp v96, v96, v96 quad_perm:[1,0,3,2] row_mask:0xf bank_mask:0xf bound_ctrl:1
	v_add_f32_dpp v97, v97, v97 quad_perm:[1,0,3,2] row_mask:0xf bank_mask:0xf bound_ctrl:1
	v_add_f32_dpp v98, v98, v98 quad_perm:[1,0,3,2] row_mask:0xf bank_mask:0xf bound_ctrl:1
	v_add_f32_dpp v99, v99, v99 quad_perm:[1,0,3,2] row_mask:0xf bank_mask:0xf bound_ctrl:1
	v_add_f32_dpp v92, v92, v92 quad_perm:[2,3,0,1] row_mask:0xf bank_mask:0xf bound_ctrl:1
	v_add_f32_dpp v93, v93, v93 quad_perm:[2,3,0,1] row_mask:0xf bank_mask:0xf bound_ctrl:1
	v_add_f32_dpp v94, v94, v94 quad_perm:[2,3,0,1] row_mask:0xf bank_mask:0xf bound_ctrl:1
	v_add_f32_dpp v95, v95, v95 quad_perm:[2,3,0,1] row_mask:0xf bank_mask:0xf bound_ctrl:1
	v_add_f32_dpp v96, v96, v96 quad_perm:[2,3,0,1] row_mask:0xf bank_mask:0xf bound_ctrl:1
	v_add_f32_dpp v97, v97, v97 quad_perm:[2,3,0,1] row_mask:0xf bank_mask:0xf bound_ctrl:1
	v_add_f32_dpp v98, v98, v98 quad_perm:[2,3,0,1] row_mask:0xf bank_mask:0xf bound_ctrl:1
	v_add_f32_dpp v99, v99, v99 quad_perm:[2,3,0,1] row_mask:0xf bank_mask:0xf bound_ctrl:1
	v_add_f32_dpp v92, v92, v92 row_half_mirror row_mask:0xf bank_mask:0xf bound_ctrl:1
	v_add_f32_dpp v93, v93, v93 row_half_mirror row_mask:0xf bank_mask:0xf bound_ctrl:1
	v_add_f32_dpp v94, v94, v94 row_half_mirror row_mask:0xf bank_mask:0xf bound_ctrl:1
	v_add_f32_dpp v95, v95, v95 row_half_mirror row_mask:0xf bank_mask:0xf bound_ctrl:1
	v_add_f32_dpp v96, v96, v96 row_half_mirror row_mask:0xf bank_mask:0xf bound_ctrl:1
	v_add_f32_dpp v97, v97, v97 row_half_mirror row_mask:0xf bank_mask:0xf bound_ctrl:1
	v_add_f32_dpp v98, v98, v98 row_half_mirror row_mask:0xf bank_mask:0xf bound_ctrl:1
	v_add_f32_dpp v99, v99, v99 row_half_mirror row_mask:0xf bank_mask:0xf bound_ctrl:1
	v_add_f32_dpp v92, v92, v92 row_mirror row_mask:0xf bank_mask:0xf bound_ctrl:1
	v_add_f32_dpp v93, v93, v93 row_mirror row_mask:0xf bank_mask:0xf bound_ctrl:1
	v_add_f32_dpp v94, v94, v94 row_mirror row_mask:0xf bank_mask:0xf bound_ctrl:1
	v_add_f32_dpp v95, v95, v95 row_mirror row_mask:0xf bank_mask:0xf bound_ctrl:1
	v_add_f32_dpp v96, v96, v96 row_mirror row_mask:0xf bank_mask:0xf bound_ctrl:1
	v_add_f32_dpp v97, v97, v97 row_mirror row_mask:0xf bank_mask:0xf bound_ctrl:1
	v_add_f32_dpp v98, v98, v98 row_mirror row_mask:0xf bank_mask:0xf bound_ctrl:1
	v_add_f32_dpp v99, v99, v99 row_mirror row_mask:0xf bank_mask:0xf bound_ctrl:1
	v_mov_b32_e32 v100, v92
	v_mov_b32_e32 v101, v93
	v_mov_b32_e32 v102, v94
	v_mov_b32_e32 v103, v95
	v_mov_b32_e32 v104, v96
	v_mov_b32_e32 v105, v97
	v_mov_b32_e32 v106, v98
	v_mov_b32_e32 v107, v99
	v_permlane16_swap_b32_e32 v92, v100
	v_permlane16_swap_b32_e32 v93, v101
	v_permlane16_swap_b32_e32 v94, v102
	v_permlane16_swap_b32_e32 v95, v103
	v_permlane16_swap_b32_e32 v96, v104
	v_permlane16_swap_b32_e32 v97, v105
	v_permlane16_swap_b32_e32 v98, v106
	v_permlane16_swap_b32_e32 v99, v107
	v_add_f32_e32 v92, v92, v100
	v_add_f32_e32 v93, v93, v101
	v_add_f32_e32 v94, v94, v102
	v_add_f32_e32 v95, v95, v103
	v_add_f32_e32 v96, v96, v104
	v_add_f32_e32 v97, v97, v105
	v_add_f32_e32 v98, v98, v106
	v_add_f32_e32 v99, v99, v107
	s_mov_b64 exec, s[74:75]
	global_store_dword v[124:125], v92, off offset:2048
	global_store_dword v[124:125], v93, off offset:2056
	global_store_dword v[124:125], v94, off offset:2064
	global_store_dword v[124:125], v95, off offset:2072
	global_store_dword v[124:125], v96, off offset:2080
	global_store_dword v[124:125], v97, off offset:2088
	global_store_dword v[124:125], v98, off offset:2096
	global_store_dword v[124:125], v99, off offset:2104
	s_mov_b64 exec, -1
	v_mul_f32_e32 v92, v76, v24
	v_mul_f32_e32 v93, v78, v24
	v_mul_f32_e32 v94, v80, v24
	v_mul_f32_e32 v95, v82, v24
	v_mul_f32_e32 v96, v84, v24
	v_mul_f32_e32 v97, v86, v24
	v_mul_f32_e32 v98, v88, v24
	v_mul_f32_e32 v99, v90, v24
	v_fmac_f32_e32 v92, v77, v25
	v_fmac_f32_e32 v93, v79, v25
	v_fmac_f32_e32 v94, v81, v25
	v_fmac_f32_e32 v95, v83, v25
	v_fmac_f32_e32 v96, v85, v25
	v_fmac_f32_e32 v97, v87, v25
	v_fmac_f32_e32 v98, v89, v25
	v_fmac_f32_e32 v99, v91, v25
	v_add_f32_dpp v92, v92, v92 quad_perm:[1,0,3,2] row_mask:0xf bank_mask:0xf bound_ctrl:1
	v_add_f32_dpp v93, v93, v93 quad_perm:[1,0,3,2] row_mask:0xf bank_mask:0xf bound_ctrl:1
	v_add_f32_dpp v94, v94, v94 quad_perm:[1,0,3,2] row_mask:0xf bank_mask:0xf bound_ctrl:1
	v_add_f32_dpp v95, v95, v95 quad_perm:[1,0,3,2] row_mask:0xf bank_mask:0xf bound_ctrl:1
	v_add_f32_dpp v96, v96, v96 quad_perm:[1,0,3,2] row_mask:0xf bank_mask:0xf bound_ctrl:1
	v_add_f32_dpp v97, v97, v97 quad_perm:[1,0,3,2] row_mask:0xf bank_mask:0xf bound_ctrl:1
	v_add_f32_dpp v98, v98, v98 quad_perm:[1,0,3,2] row_mask:0xf bank_mask:0xf bound_ctrl:1
	v_add_f32_dpp v99, v99, v99 quad_perm:[1,0,3,2] row_mask:0xf bank_mask:0xf bound_ctrl:1
	v_add_f32_dpp v92, v92, v92 quad_perm:[2,3,0,1] row_mask:0xf bank_mask:0xf bound_ctrl:1
	v_add_f32_dpp v93, v93, v93 quad_perm:[2,3,0,1] row_mask:0xf bank_mask:0xf bound_ctrl:1
	v_add_f32_dpp v94, v94, v94 quad_perm:[2,3,0,1] row_mask:0xf bank_mask:0xf bound_ctrl:1
	v_add_f32_dpp v95, v95, v95 quad_perm:[2,3,0,1] row_mask:0xf bank_mask:0xf bound_ctrl:1
	v_add_f32_dpp v96, v96, v96 quad_perm:[2,3,0,1] row_mask:0xf bank_mask:0xf bound_ctrl:1
	v_add_f32_dpp v97, v97, v97 quad_perm:[2,3,0,1] row_mask:0xf bank_mask:0xf bound_ctrl:1
	v_add_f32_dpp v98, v98, v98 quad_perm:[2,3,0,1] row_mask:0xf bank_mask:0xf bound_ctrl:1
	v_add_f32_dpp v99, v99, v99 quad_perm:[2,3,0,1] row_mask:0xf bank_mask:0xf bound_ctrl:1
	v_add_f32_dpp v92, v92, v92 row_half_mirror row_mask:0xf bank_mask:0xf bound_ctrl:1
	v_add_f32_dpp v93, v93, v93 row_half_mirror row_mask:0xf bank_mask:0xf bound_ctrl:1
	v_add_f32_dpp v94, v94, v94 row_half_mirror row_mask:0xf bank_mask:0xf bound_ctrl:1
	v_add_f32_dpp v95, v95, v95 row_half_mirror row_mask:0xf bank_mask:0xf bound_ctrl:1
	v_add_f32_dpp v96, v96, v96 row_half_mirror row_mask:0xf bank_mask:0xf bound_ctrl:1
	v_add_f32_dpp v97, v97, v97 row_half_mirror row_mask:0xf bank_mask:0xf bound_ctrl:1
	v_add_f32_dpp v98, v98, v98 row_half_mirror row_mask:0xf bank_mask:0xf bound_ctrl:1
	v_add_f32_dpp v99, v99, v99 row_half_mirror row_mask:0xf bank_mask:0xf bound_ctrl:1
	v_add_f32_dpp v92, v92, v92 row_mirror row_mask:0xf bank_mask:0xf bound_ctrl:1
	v_add_f32_dpp v93, v93, v93 row_mirror row_mask:0xf bank_mask:0xf bound_ctrl:1
	v_add_f32_dpp v94, v94, v94 row_mirror row_mask:0xf bank_mask:0xf bound_ctrl:1
	v_add_f32_dpp v95, v95, v95 row_mirror row_mask:0xf bank_mask:0xf bound_ctrl:1
	v_add_f32_dpp v96, v96, v96 row_mirror row_mask:0xf bank_mask:0xf bound_ctrl:1
	v_add_f32_dpp v97, v97, v97 row_mirror row_mask:0xf bank_mask:0xf bound_ctrl:1
	v_add_f32_dpp v98, v98, v98 row_mirror row_mask:0xf bank_mask:0xf bound_ctrl:1
	v_add_f32_dpp v99, v99, v99 row_mirror row_mask:0xf bank_mask:0xf bound_ctrl:1
	v_mov_b32_e32 v100, v92
	v_mov_b32_e32 v101, v93
	v_mov_b32_e32 v102, v94
	v_mov_b32_e32 v103, v95
	v_mov_b32_e32 v104, v96
	v_mov_b32_e32 v105, v97
	v_mov_b32_e32 v106, v98
	v_mov_b32_e32 v107, v99
	v_permlane16_swap_b32_e32 v92, v100
	v_permlane16_swap_b32_e32 v93, v101
	v_permlane16_swap_b32_e32 v94, v102
	v_permlane16_swap_b32_e32 v95, v103
	v_permlane16_swap_b32_e32 v96, v104
	v_permlane16_swap_b32_e32 v97, v105
	v_permlane16_swap_b32_e32 v98, v106
	v_permlane16_swap_b32_e32 v99, v107
	v_add_f32_e32 v92, v92, v100
	v_add_f32_e32 v93, v93, v101
	v_add_f32_e32 v94, v94, v102
	v_add_f32_e32 v95, v95, v103
	v_add_f32_e32 v96, v96, v104
	v_add_f32_e32 v97, v97, v105
	v_add_f32_e32 v98, v98, v106
	v_add_f32_e32 v99, v99, v107
	v_pk_mul_f32 v[76:77], v[76:77], v[26:27]
	v_pk_mul_f32 v[78:79], v[78:79], v[26:27]
	v_pk_mul_f32 v[80:81], v[80:81], v[26:27]
	v_pk_mul_f32 v[82:83], v[82:83], v[26:27]
	v_pk_mul_f32 v[84:85], v[84:85], v[26:27]
	v_pk_mul_f32 v[86:87], v[86:87], v[26:27]
	v_pk_mul_f32 v[88:89], v[88:89], v[26:27]
	v_pk_mul_f32 v[90:91], v[90:91], v[26:27]
	v_fmac_f32_e32 v76, v92, v28
	v_fmac_f32_e32 v77, v92, v29
	v_fmac_f32_e32 v78, v93, v28
	v_fmac_f32_e32 v79, v93, v29
	v_fmac_f32_e32 v80, v94, v28
	v_fmac_f32_e32 v81, v94, v29
	v_fmac_f32_e32 v82, v95, v28
	v_fmac_f32_e32 v83, v95, v29
	v_fmac_f32_e32 v84, v96, v28
	v_fmac_f32_e32 v85, v96, v29
	v_fmac_f32_e32 v86, v97, v28
	v_fmac_f32_e32 v87, v97, v29
	v_fmac_f32_e32 v88, v98, v28
	v_fmac_f32_e32 v89, v98, v29
	v_fmac_f32_e32 v90, v99, v28
	v_fmac_f32_e32 v91, v99, v29
	v_fmac_f32_e32 v76, v60, v30
	v_fmac_f32_e32 v77, v60, v31
	v_fmac_f32_e32 v78, v61, v30
	v_fmac_f32_e32 v79, v61, v31
	v_fmac_f32_e32 v80, v62, v30
	v_fmac_f32_e32 v81, v62, v31
	v_fmac_f32_e32 v82, v63, v30
	v_fmac_f32_e32 v83, v63, v31
	v_fmac_f32_e32 v84, v64, v30
	v_fmac_f32_e32 v85, v64, v31
	v_fmac_f32_e32 v86, v65, v30
	v_fmac_f32_e32 v87, v65, v31
	v_fmac_f32_e32 v88, v66, v30
	v_fmac_f32_e32 v89, v66, v31
	v_fmac_f32_e32 v90, v67, v30
	v_fmac_f32_e32 v91, v67, v31
	v_mul_f32_e32 v92, v76, v32
	v_mul_f32_e32 v93, v78, v32
	v_mul_f32_e32 v94, v80, v32
	v_mul_f32_e32 v95, v82, v32
	v_mul_f32_e32 v96, v84, v32
	v_mul_f32_e32 v97, v86, v32
	v_mul_f32_e32 v98, v88, v32
	v_mul_f32_e32 v99, v90, v32
	v_fmac_f32_e32 v92, v77, v33
	v_fmac_f32_e32 v93, v79, v33
	v_fmac_f32_e32 v94, v81, v33
	v_fmac_f32_e32 v95, v83, v33
	v_fmac_f32_e32 v96, v85, v33
	v_fmac_f32_e32 v97, v87, v33
	v_fmac_f32_e32 v98, v89, v33
	v_fmac_f32_e32 v99, v91, v33
	v_add_f32_dpp v92, v92, v92 quad_perm:[1,0,3,2] row_mask:0xf bank_mask:0xf bound_ctrl:1
	v_add_f32_dpp v93, v93, v93 quad_perm:[1,0,3,2] row_mask:0xf bank_mask:0xf bound_ctrl:1
	v_add_f32_dpp v94, v94, v94 quad_perm:[1,0,3,2] row_mask:0xf bank_mask:0xf bound_ctrl:1
	v_add_f32_dpp v95, v95, v95 quad_perm:[1,0,3,2] row_mask:0xf bank_mask:0xf bound_ctrl:1
	v_add_f32_dpp v96, v96, v96 quad_perm:[1,0,3,2] row_mask:0xf bank_mask:0xf bound_ctrl:1
	v_add_f32_dpp v97, v97, v97 quad_perm:[1,0,3,2] row_mask:0xf bank_mask:0xf bound_ctrl:1
	v_add_f32_dpp v98, v98, v98 quad_perm:[1,0,3,2] row_mask:0xf bank_mask:0xf bound_ctrl:1
	v_add_f32_dpp v99, v99, v99 quad_perm:[1,0,3,2] row_mask:0xf bank_mask:0xf bound_ctrl:1
	v_add_f32_dpp v92, v92, v92 quad_perm:[2,3,0,1] row_mask:0xf bank_mask:0xf bound_ctrl:1
	v_add_f32_dpp v93, v93, v93 quad_perm:[2,3,0,1] row_mask:0xf bank_mask:0xf bound_ctrl:1
	v_add_f32_dpp v94, v94, v94 quad_perm:[2,3,0,1] row_mask:0xf bank_mask:0xf bound_ctrl:1
	v_add_f32_dpp v95, v95, v95 quad_perm:[2,3,0,1] row_mask:0xf bank_mask:0xf bound_ctrl:1
	v_add_f32_dpp v96, v96, v96 quad_perm:[2,3,0,1] row_mask:0xf bank_mask:0xf bound_ctrl:1
	v_add_f32_dpp v97, v97, v97 quad_perm:[2,3,0,1] row_mask:0xf bank_mask:0xf bound_ctrl:1
	v_add_f32_dpp v98, v98, v98 quad_perm:[2,3,0,1] row_mask:0xf bank_mask:0xf bound_ctrl:1
	v_add_f32_dpp v99, v99, v99 quad_perm:[2,3,0,1] row_mask:0xf bank_mask:0xf bound_ctrl:1
	v_add_f32_dpp v92, v92, v92 row_half_mirror row_mask:0xf bank_mask:0xf bound_ctrl:1
	v_add_f32_dpp v93, v93, v93 row_half_mirror row_mask:0xf bank_mask:0xf bound_ctrl:1
	v_add_f32_dpp v94, v94, v94 row_half_mirror row_mask:0xf bank_mask:0xf bound_ctrl:1
	v_add_f32_dpp v95, v95, v95 row_half_mirror row_mask:0xf bank_mask:0xf bound_ctrl:1
	v_add_f32_dpp v96, v96, v96 row_half_mirror row_mask:0xf bank_mask:0xf bound_ctrl:1
	v_add_f32_dpp v97, v97, v97 row_half_mirror row_mask:0xf bank_mask:0xf bound_ctrl:1
	v_add_f32_dpp v98, v98, v98 row_half_mirror row_mask:0xf bank_mask:0xf bound_ctrl:1
	v_add_f32_dpp v99, v99, v99 row_half_mirror row_mask:0xf bank_mask:0xf bound_ctrl:1
	v_add_f32_dpp v92, v92, v92 row_mirror row_mask:0xf bank_mask:0xf bound_ctrl:1
	v_add_f32_dpp v93, v93, v93 row_mirror row_mask:0xf bank_mask:0xf bound_ctrl:1
	v_add_f32_dpp v94, v94, v94 row_mirror row_mask:0xf bank_mask:0xf bound_ctrl:1
	v_add_f32_dpp v95, v95, v95 row_mirror row_mask:0xf bank_mask:0xf bound_ctrl:1
	v_add_f32_dpp v96, v96, v96 row_mirror row_mask:0xf bank_mask:0xf bound_ctrl:1
	v_add_f32_dpp v97, v97, v97 row_mirror row_mask:0xf bank_mask:0xf bound_ctrl:1
	v_add_f32_dpp v98, v98, v98 row_mirror row_mask:0xf bank_mask:0xf bound_ctrl:1
	v_add_f32_dpp v99, v99, v99 row_mirror row_mask:0xf bank_mask:0xf bound_ctrl:1
	v_mov_b32_e32 v100, v92
	v_mov_b32_e32 v101, v93
	v_mov_b32_e32 v102, v94
	v_mov_b32_e32 v103, v95
	v_mov_b32_e32 v104, v96
	v_mov_b32_e32 v105, v97
	v_mov_b32_e32 v106, v98
	v_mov_b32_e32 v107, v99
	v_permlane16_swap_b32_e32 v92, v100
	v_permlane16_swap_b32_e32 v93, v101
	v_permlane16_swap_b32_e32 v94, v102
	v_permlane16_swap_b32_e32 v95, v103
	v_permlane16_swap_b32_e32 v96, v104
	v_permlane16_swap_b32_e32 v97, v105
	v_permlane16_swap_b32_e32 v98, v106
	v_permlane16_swap_b32_e32 v99, v107
	v_add_f32_e32 v92, v92, v100
	v_add_f32_e32 v93, v93, v101
	v_add_f32_e32 v94, v94, v102
	v_add_f32_e32 v95, v95, v103
	v_add_f32_e32 v96, v96, v104
	v_add_f32_e32 v97, v97, v105
	v_add_f32_e32 v98, v98, v106
	v_add_f32_e32 v99, v99, v107
	s_mov_b64 exec, s[74:75]
	global_store_dword v[126:127], v92, off offset:0
	global_store_dword v[126:127], v93, off offset:8
	global_store_dword v[126:127], v94, off offset:16
	global_store_dword v[126:127], v95, off offset:24
	global_store_dword v[126:127], v96, off offset:32
	global_store_dword v[126:127], v97, off offset:40
	global_store_dword v[126:127], v98, off offset:48
	global_store_dword v[126:127], v99, off offset:56
	s_mov_b64 exec, -1
	v_mul_f32_e32 v92, v76, v34
	v_mul_f32_e32 v93, v78, v34
	v_mul_f32_e32 v94, v80, v34
	v_mul_f32_e32 v95, v82, v34
	v_mul_f32_e32 v96, v84, v34
	v_mul_f32_e32 v97, v86, v34
	v_mul_f32_e32 v98, v88, v34
	v_mul_f32_e32 v99, v90, v34
	v_fmac_f32_e32 v92, v77, v35
	v_fmac_f32_e32 v93, v79, v35
	v_fmac_f32_e32 v94, v81, v35
	v_fmac_f32_e32 v95, v83, v35
	v_fmac_f32_e32 v96, v85, v35
	v_fmac_f32_e32 v97, v87, v35
	v_fmac_f32_e32 v98, v89, v35
	v_fmac_f32_e32 v99, v91, v35
	v_add_f32_dpp v92, v92, v92 quad_perm:[1,0,3,2] row_mask:0xf bank_mask:0xf bound_ctrl:1
	v_add_f32_dpp v93, v93, v93 quad_perm:[1,0,3,2] row_mask:0xf bank_mask:0xf bound_ctrl:1
	v_add_f32_dpp v94, v94, v94 quad_perm:[1,0,3,2] row_mask:0xf bank_mask:0xf bound_ctrl:1
	v_add_f32_dpp v95, v95, v95 quad_perm:[1,0,3,2] row_mask:0xf bank_mask:0xf bound_ctrl:1
	v_add_f32_dpp v96, v96, v96 quad_perm:[1,0,3,2] row_mask:0xf bank_mask:0xf bound_ctrl:1
	v_add_f32_dpp v97, v97, v97 quad_perm:[1,0,3,2] row_mask:0xf bank_mask:0xf bound_ctrl:1
	v_add_f32_dpp v98, v98, v98 quad_perm:[1,0,3,2] row_mask:0xf bank_mask:0xf bound_ctrl:1
	v_add_f32_dpp v99, v99, v99 quad_perm:[1,0,3,2] row_mask:0xf bank_mask:0xf bound_ctrl:1
	v_add_f32_dpp v92, v92, v92 quad_perm:[2,3,0,1] row_mask:0xf bank_mask:0xf bound_ctrl:1
	v_add_f32_dpp v93, v93, v93 quad_perm:[2,3,0,1] row_mask:0xf bank_mask:0xf bound_ctrl:1
	v_add_f32_dpp v94, v94, v94 quad_perm:[2,3,0,1] row_mask:0xf bank_mask:0xf bound_ctrl:1
	v_add_f32_dpp v95, v95, v95 quad_perm:[2,3,0,1] row_mask:0xf bank_mask:0xf bound_ctrl:1
	v_add_f32_dpp v96, v96, v96 quad_perm:[2,3,0,1] row_mask:0xf bank_mask:0xf bound_ctrl:1
	v_add_f32_dpp v97, v97, v97 quad_perm:[2,3,0,1] row_mask:0xf bank_mask:0xf bound_ctrl:1
	v_add_f32_dpp v98, v98, v98 quad_perm:[2,3,0,1] row_mask:0xf bank_mask:0xf bound_ctrl:1
	v_add_f32_dpp v99, v99, v99 quad_perm:[2,3,0,1] row_mask:0xf bank_mask:0xf bound_ctrl:1
	v_add_f32_dpp v92, v92, v92 row_half_mirror row_mask:0xf bank_mask:0xf bound_ctrl:1
	v_add_f32_dpp v93, v93, v93 row_half_mirror row_mask:0xf bank_mask:0xf bound_ctrl:1
	v_add_f32_dpp v94, v94, v94 row_half_mirror row_mask:0xf bank_mask:0xf bound_ctrl:1
	v_add_f32_dpp v95, v95, v95 row_half_mirror row_mask:0xf bank_mask:0xf bound_ctrl:1
	v_add_f32_dpp v96, v96, v96 row_half_mirror row_mask:0xf bank_mask:0xf bound_ctrl:1
	v_add_f32_dpp v97, v97, v97 row_half_mirror row_mask:0xf bank_mask:0xf bound_ctrl:1
	v_add_f32_dpp v98, v98, v98 row_half_mirror row_mask:0xf bank_mask:0xf bound_ctrl:1
	v_add_f32_dpp v99, v99, v99 row_half_mirror row_mask:0xf bank_mask:0xf bound_ctrl:1
	v_add_f32_dpp v92, v92, v92 row_mirror row_mask:0xf bank_mask:0xf bound_ctrl:1
	v_add_f32_dpp v93, v93, v93 row_mirror row_mask:0xf bank_mask:0xf bound_ctrl:1
	v_add_f32_dpp v94, v94, v94 row_mirror row_mask:0xf bank_mask:0xf bound_ctrl:1
	v_add_f32_dpp v95, v95, v95 row_mirror row_mask:0xf bank_mask:0xf bound_ctrl:1
	v_add_f32_dpp v96, v96, v96 row_mirror row_mask:0xf bank_mask:0xf bound_ctrl:1
	v_add_f32_dpp v97, v97, v97 row_mirror row_mask:0xf bank_mask:0xf bound_ctrl:1
	v_add_f32_dpp v98, v98, v98 row_mirror row_mask:0xf bank_mask:0xf bound_ctrl:1
	v_add_f32_dpp v99, v99, v99 row_mirror row_mask:0xf bank_mask:0xf bound_ctrl:1
	v_mov_b32_e32 v100, v92
	v_mov_b32_e32 v101, v93
	v_mov_b32_e32 v102, v94
	v_mov_b32_e32 v103, v95
	v_mov_b32_e32 v104, v96
	v_mov_b32_e32 v105, v97
	v_mov_b32_e32 v106, v98
	v_mov_b32_e32 v107, v99
	v_permlane16_swap_b32_e32 v92, v100
	v_permlane16_swap_b32_e32 v93, v101
	v_permlane16_swap_b32_e32 v94, v102
	v_permlane16_swap_b32_e32 v95, v103
	v_permlane16_swap_b32_e32 v96, v104
	v_permlane16_swap_b32_e32 v97, v105
	v_permlane16_swap_b32_e32 v98, v106
	v_permlane16_swap_b32_e32 v99, v107
	v_add_f32_e32 v92, v92, v100
	v_add_f32_e32 v93, v93, v101
	v_add_f32_e32 v94, v94, v102
	v_add_f32_e32 v95, v95, v103
	v_add_f32_e32 v96, v96, v104
	v_add_f32_e32 v97, v97, v105
	v_add_f32_e32 v98, v98, v106
	v_add_f32_e32 v99, v99, v107
	v_pk_mul_f32 v[76:77], v[76:77], v[36:37]
	v_pk_mul_f32 v[78:79], v[78:79], v[36:37]
	v_pk_mul_f32 v[80:81], v[80:81], v[36:37]
	v_pk_mul_f32 v[82:83], v[82:83], v[36:37]
	v_pk_mul_f32 v[84:85], v[84:85], v[36:37]
	v_pk_mul_f32 v[86:87], v[86:87], v[36:37]
	v_pk_mul_f32 v[88:89], v[88:89], v[36:37]
	v_pk_mul_f32 v[90:91], v[90:91], v[36:37]
	v_fmac_f32_e32 v76, v92, v38
	v_fmac_f32_e32 v77, v92, v39
	v_fmac_f32_e32 v78, v93, v38
	v_fmac_f32_e32 v79, v93, v39
	v_fmac_f32_e32 v80, v94, v38
	v_fmac_f32_e32 v81, v94, v39
	v_fmac_f32_e32 v82, v95, v38
	v_fmac_f32_e32 v83, v95, v39
	v_fmac_f32_e32 v84, v96, v38
	v_fmac_f32_e32 v85, v96, v39
	v_fmac_f32_e32 v86, v97, v38
	v_fmac_f32_e32 v87, v97, v39
	v_fmac_f32_e32 v88, v98, v38
	v_fmac_f32_e32 v89, v98, v39
	v_fmac_f32_e32 v90, v99, v38
	v_fmac_f32_e32 v91, v99, v39
	v_fmac_f32_e32 v76, v68, v40
	v_fmac_f32_e32 v77, v68, v41
	v_fmac_f32_e32 v78, v69, v40
	v_fmac_f32_e32 v79, v69, v41
	v_fmac_f32_e32 v80, v70, v40
	v_fmac_f32_e32 v81, v70, v41
	v_fmac_f32_e32 v82, v71, v40
	v_fmac_f32_e32 v83, v71, v41
	v_fmac_f32_e32 v84, v72, v40
	v_fmac_f32_e32 v85, v72, v41
	v_fmac_f32_e32 v86, v73, v40
	v_fmac_f32_e32 v87, v73, v41
	v_fmac_f32_e32 v88, v74, v40
	v_fmac_f32_e32 v89, v74, v41
	v_fmac_f32_e32 v90, v75, v40
	v_fmac_f32_e32 v91, v75, v41
	v_mul_f32_e32 v92, v76, v42
	v_mul_f32_e32 v93, v78, v42
	v_mul_f32_e32 v94, v80, v42
	v_mul_f32_e32 v95, v82, v42
	v_mul_f32_e32 v96, v84, v42
	v_mul_f32_e32 v97, v86, v42
	v_mul_f32_e32 v98, v88, v42
	v_mul_f32_e32 v99, v90, v42
	v_fmac_f32_e32 v92, v77, v43
	v_fmac_f32_e32 v93, v79, v43
	v_fmac_f32_e32 v94, v81, v43
	v_fmac_f32_e32 v95, v83, v43
	v_fmac_f32_e32 v96, v85, v43
	v_fmac_f32_e32 v97, v87, v43
	v_fmac_f32_e32 v98, v89, v43
	v_fmac_f32_e32 v99, v91, v43
	v_add_f32_dpp v92, v92, v92 quad_perm:[1,0,3,2] row_mask:0xf bank_mask:0xf bound_ctrl:1
	v_add_f32_dpp v93, v93, v93 quad_perm:[1,0,3,2] row_mask:0xf bank_mask:0xf bound_ctrl:1
	v_add_f32_dpp v94, v94, v94 quad_perm:[1,0,3,2] row_mask:0xf bank_mask:0xf bound_ctrl:1
	v_add_f32_dpp v95, v95, v95 quad_perm:[1,0,3,2] row_mask:0xf bank_mask:0xf bound_ctrl:1
	v_add_f32_dpp v96, v96, v96 quad_perm:[1,0,3,2] row_mask:0xf bank_mask:0xf bound_ctrl:1
	v_add_f32_dpp v97, v97, v97 quad_perm:[1,0,3,2] row_mask:0xf bank_mask:0xf bound_ctrl:1
	v_add_f32_dpp v98, v98, v98 quad_perm:[1,0,3,2] row_mask:0xf bank_mask:0xf bound_ctrl:1
	v_add_f32_dpp v99, v99, v99 quad_perm:[1,0,3,2] row_mask:0xf bank_mask:0xf bound_ctrl:1
	v_add_f32_dpp v92, v92, v92 quad_perm:[2,3,0,1] row_mask:0xf bank_mask:0xf bound_ctrl:1
	v_add_f32_dpp v93, v93, v93 quad_perm:[2,3,0,1] row_mask:0xf bank_mask:0xf bound_ctrl:1
	v_add_f32_dpp v94, v94, v94 quad_perm:[2,3,0,1] row_mask:0xf bank_mask:0xf bound_ctrl:1
	v_add_f32_dpp v95, v95, v95 quad_perm:[2,3,0,1] row_mask:0xf bank_mask:0xf bound_ctrl:1
	v_add_f32_dpp v96, v96, v96 quad_perm:[2,3,0,1] row_mask:0xf bank_mask:0xf bound_ctrl:1
	v_add_f32_dpp v97, v97, v97 quad_perm:[2,3,0,1] row_mask:0xf bank_mask:0xf bound_ctrl:1
	v_add_f32_dpp v98, v98, v98 quad_perm:[2,3,0,1] row_mask:0xf bank_mask:0xf bound_ctrl:1
	v_add_f32_dpp v99, v99, v99 quad_perm:[2,3,0,1] row_mask:0xf bank_mask:0xf bound_ctrl:1
	v_add_f32_dpp v92, v92, v92 row_half_mirror row_mask:0xf bank_mask:0xf bound_ctrl:1
	v_add_f32_dpp v93, v93, v93 row_half_mirror row_mask:0xf bank_mask:0xf bound_ctrl:1
	v_add_f32_dpp v94, v94, v94 row_half_mirror row_mask:0xf bank_mask:0xf bound_ctrl:1
	v_add_f32_dpp v95, v95, v95 row_half_mirror row_mask:0xf bank_mask:0xf bound_ctrl:1
	v_add_f32_dpp v96, v96, v96 row_half_mirror row_mask:0xf bank_mask:0xf bound_ctrl:1
	v_add_f32_dpp v97, v97, v97 row_half_mirror row_mask:0xf bank_mask:0xf bound_ctrl:1
	v_add_f32_dpp v98, v98, v98 row_half_mirror row_mask:0xf bank_mask:0xf bound_ctrl:1
	v_add_f32_dpp v99, v99, v99 row_half_mirror row_mask:0xf bank_mask:0xf bound_ctrl:1
	v_add_f32_dpp v92, v92, v92 row_mirror row_mask:0xf bank_mask:0xf bound_ctrl:1
	v_add_f32_dpp v93, v93, v93 row_mirror row_mask:0xf bank_mask:0xf bound_ctrl:1
	v_add_f32_dpp v94, v94, v94 row_mirror row_mask:0xf bank_mask:0xf bound_ctrl:1
	v_add_f32_dpp v95, v95, v95 row_mirror row_mask:0xf bank_mask:0xf bound_ctrl:1
	v_add_f32_dpp v96, v96, v96 row_mirror row_mask:0xf bank_mask:0xf bound_ctrl:1
	v_add_f32_dpp v97, v97, v97 row_mirror row_mask:0xf bank_mask:0xf bound_ctrl:1
	v_add_f32_dpp v98, v98, v98 row_mirror row_mask:0xf bank_mask:0xf bound_ctrl:1
	v_add_f32_dpp v99, v99, v99 row_mirror row_mask:0xf bank_mask:0xf bound_ctrl:1
	v_mov_b32_e32 v100, v92
	v_mov_b32_e32 v101, v93
	v_mov_b32_e32 v102, v94
	v_mov_b32_e32 v103, v95
	v_mov_b32_e32 v104, v96
	v_mov_b32_e32 v105, v97
	v_mov_b32_e32 v106, v98
	v_mov_b32_e32 v107, v99
	v_permlane16_swap_b32_e32 v92, v100
	v_permlane16_swap_b32_e32 v93, v101
	v_permlane16_swap_b32_e32 v94, v102
	v_permlane16_swap_b32_e32 v95, v103
	v_permlane16_swap_b32_e32 v96, v104
	v_permlane16_swap_b32_e32 v97, v105
	v_permlane16_swap_b32_e32 v98, v106
	v_permlane16_swap_b32_e32 v99, v107
	v_add_f32_e32 v92, v92, v100
	v_add_f32_e32 v93, v93, v101
	v_add_f32_e32 v94, v94, v102
	v_add_f32_e32 v95, v95, v103
	v_add_f32_e32 v96, v96, v104
	v_add_f32_e32 v97, v97, v105
	v_add_f32_e32 v98, v98, v106
	v_add_f32_e32 v99, v99, v107
	s_mov_b64 exec, s[74:75]
	global_store_dword v[126:127], v92, off offset:2048
	global_store_dword v[126:127], v93, off offset:2056
	global_store_dword v[126:127], v94, off offset:2064
	global_store_dword v[126:127], v95, off offset:2072
	global_store_dword v[126:127], v96, off offset:2080
	global_store_dword v[126:127], v97, off offset:2088
	global_store_dword v[126:127], v98, off offset:2096
	global_store_dword v[126:127], v99, off offset:2104
	s_mov_b64 exec, -1
	global_store_dwordx2 v118, v[76:77], s[10:11] offset:0
	global_store_dwordx2 v118, v[78:79], s[10:11] offset:512
	global_store_dwordx2 v118, v[80:81], s[10:11] offset:1024
	global_store_dwordx2 v118, v[82:83], s[10:11] offset:1536
	global_store_dwordx2 v118, v[84:85], s[10:11] offset:2048
	global_store_dwordx2 v118, v[86:87], s[10:11] offset:2560
	global_store_dwordx2 v118, v[88:89], s[10:11] offset:3072
	global_store_dwordx2 v118, v[90:91], s[10:11] offset:3584
